# dense softmax: hazard padding replaced by instruction ordering (s_nop removed from the common path), cross-half exchanges deferred
# speedup vs baseline: 1.0213x; 1.0117x over previous
; __device__ __forceinline__ void partialSM(f32x16& p0, f32x16& p1, float& m_reg, float& mn, float& alpha) {
;   constexpr float C = SCALE * 1.4426950408889634f;
;   float pmax = p0[0];
; #pragma unroll
;   for (int r = 1; r < 16; ++r) pmax = fmaxf(pmax, p0[r]);
; #pragma unroll
;   for (int r = 0; r < 16; ++r) pmax = fmaxf(pmax, p1[r]);
;   { auto rr = __builtin_amdgcn_permlane32_swap(__float_as_uint(pmax), __float_as_uint(pmax), false, false);
;     pmax = fmaxf(__uint_as_float(rr[0]), __uint_as_float(rr[1])); }
;   if (__builtin_expect(__all(pmax - m_reg <= THR / SCALE), 1)) { mn = m_reg; alpha = 1.f; }
;   else { mn = fmaxf(m_reg, pmax); alpha = __builtin_amdgcn_exp2f((m_reg - mn) * C); m_reg = mn; }
.Lda_y0:
	s_barrier
	v_max3_f32 v190, v80, v81, v82
	v_max3_f32 v191, v64, v65, v66
	v_max3_f32 v190, v190, v83, v84
	v_max3_f32 v191, v191, v67, v68
	v_max3_f32 v190, v190, v85, v86
	v_max3_f32 v191, v191, v69, v70
	v_max3_f32 v190, v190, v87, v88
	v_max3_f32 v191, v191, v71, v72
	v_max3_f32 v190, v190, v89, v90
	v_max3_f32 v191, v191, v73, v74
	v_max3_f32 v190, v190, v91, v92
	v_max3_f32 v191, v191, v75, v76
	v_max3_f32 v190, v190, v93, v94
	v_max3_f32 v191, v191, v77, v78
	v_max3_f32 v190, v190, v95, v79
	v_max_f32_e32 v190, v190, v191
	v_sub_f32_e32 v215, v190, v174
	v_cmp_ge_f32_e32 vcc, s86, v215
	s_nop 0
	s_cmp_eq_u64 vcc, exec
	s_cbranch_scc1 .Lda_common_0
	v_mov_b32_e32 v191, v190
	s_nop 1
	v_permlane32_swap_b32_e32 v190, v191
	s_nop 0
	v_max_f32_e32 v212, v190, v191
	v_max_f32_e32 v191, v174, v212
	v_sub_f32_e32 v215, v174, v191
	v_mul_f32_e32 v215, s92, v215
	v_exp_f32_e32 v213, v215
	v_mov_b32_e32 v174, v191
	v_mul_f32_e32 v214, 0xbe0293ee, v174
	v_mul_f32_e32 v175, v175, v213
	s_and_saveexec_b64 s[12:13], s[40:41]
	ds_write_b32 v199, v213 offset:128
	s_or_b64 exec, exec, s[12:13]
	s_waitcnt lgkmcnt(0)
	v_add_u32_e32 v215, v99, v96
	ds_read_b128 v[228:231], v215 offset:128
	ds_read_b128 v[232:235], v215 offset:160
	ds_read_b128 v[236:239], v215 offset:192
	ds_read_b128 v[240:243], v215 offset:224
	s_waitcnt lgkmcnt(0)
	v_pk_mul_f32 v[0:1], v[0:1], v[228:229]
	v_pk_mul_f32 v[2:3], v[2:3], v[230:231]
	v_pk_mul_f32 v[4:5], v[4:5], v[232:233]
	v_pk_mul_f32 v[6:7], v[6:7], v[234:235]
	v_pk_mul_f32 v[8:9], v[8:9], v[236:237]
	v_pk_mul_f32 v[10:11], v[10:11], v[238:239]
	v_pk_mul_f32 v[12:13], v[12:13], v[240:241]
	v_pk_mul_f32 v[14:15], v[14:15], v[242:243]
	v_pk_mul_f32 v[48:49], v[48:49], v[228:229]
	v_pk_mul_f32 v[50:51], v[50:51], v[230:231]
	v_pk_mul_f32 v[52:53], v[52:53], v[232:233]
	v_pk_mul_f32 v[54:55], v[54:55], v[234:235]
	v_pk_mul_f32 v[56:57], v[56:57], v[236:237]
	v_pk_mul_f32 v[58:59], v[58:59], v[238:239]
	v_pk_mul_f32 v[60:61], v[60:61], v[240:241]
	v_pk_mul_f32 v[62:63], v[62:63], v[242:243]
	v_pk_mul_f32 v[32:33], v[32:33], v[228:229]
	v_pk_mul_f32 v[34:35], v[34:35], v[230:231]
	v_pk_mul_f32 v[36:37], v[36:37], v[232:233]
	v_pk_mul_f32 v[38:39], v[38:39], v[234:235]
	v_pk_mul_f32 v[40:41], v[40:41], v[236:237]
	v_pk_mul_f32 v[42:43], v[42:43], v[238:239]
	v_pk_mul_f32 v[44:45], v[44:45], v[240:241]
	v_pk_mul_f32 v[46:47], v[46:47], v[242:243]
	v_pk_mul_f32 v[16:17], v[16:17], v[228:229]
	v_pk_mul_f32 v[18:19], v[18:19], v[230:231]
	v_pk_mul_f32 v[20:21], v[20:21], v[232:233]
	v_pk_mul_f32 v[22:23], v[22:23], v[234:235]
	v_pk_mul_f32 v[24:25], v[24:25], v[236:237]
	v_pk_mul_f32 v[26:27], v[26:27], v[238:239]
	v_pk_mul_f32 v[28:29], v[28:29], v[240:241]
	v_pk_mul_f32 v[30:31], v[30:31], v[242:243]

; __device__ __forceinline__ void finishSM(f32x16& p0, f32x16& p1, float alpha, float& l_reg, bf16x8& pa0, bf16x8& pa1, bf16x8& pa2, bf16x8& pa3) {
; #pragma unroll
;   for (int r = 0; r < 16; ++r) p1[r] = __builtin_amdgcn_exp2f(p1[r]);
;   float ps = 0;
; #pragma unroll
;   for (int r = 0; r < 16; ++r) ps += p0[r];
; #pragma unroll
;   for (int r = 0; r < 16; ++r) ps += p1[r];
;   { auto rr = __builtin_amdgcn_permlane32_swap(__float_as_uint(ps), __float_as_uint(ps), false, false);
;     ps = __uint_as_float(rr[0]) + __uint_as_float(rr[1]); }
;   l_reg = l_reg * alpha + ps;
;     ...
;   PK4(p0, 0, pa0); PK4(p0, 8, pa1); PK4(p1, 0, pa2); PK4(p1, 8, pa3);
;     ...
; }
; __device__ __forceinline__ void qkt(f32x16& p0, f32x16& p1, const bf16_t* Ks, const bf16x8* qr, int r32, int hi) {
;   p0 = f32x16{}; p1 = f32x16{};
; #pragma unroll
;   for (int d0 = 0; d0 < 8; ++d0) { int cb = (d0 * 16 + hi * 8) * 2;
;     bf16x8 b0 = *reinterpret_cast<const bf16x8*>((const char*)Ks + KSWZ(r32, cb));
;     bf16x8 b1 = *reinterpret_cast<const bf16x8*>((const char*)Ks + KSWZ(32 + r32, cb));
;     p0 = __builtin_amdgcn_mfma_f32_32x32x16_bf16(b0, qr[d0], p0, 0, 0, 0);
;     p1 = __builtin_amdgcn_mfma_f32_32x32x16_bf16(b1, qr[d0], p1, 0, 0, 0); }
; }
.Lda_noresc_0:
	v_exp_f32_e32 v80, v80
	v_exp_f32_e32 v81, v81
	v_exp_f32_e32 v82, v82
	v_exp_f32_e32 v83, v83
	v_exp_f32_e32 v84, v84
	v_exp_f32_e32 v85, v85
	v_exp_f32_e32 v86, v86
	v_exp_f32_e32 v87, v87
	v_exp_f32_e32 v88, v88
	v_exp_f32_e32 v89, v89
	v_exp_f32_e32 v90, v90
	v_exp_f32_e32 v91, v91
	v_exp_f32_e32 v92, v92
	v_exp_f32_e32 v93, v93
	v_exp_f32_e32 v94, v94
	v_exp_f32_e32 v95, v95
	v_exp_f32_e32 v64, v64
	v_exp_f32_e32 v65, v65
	v_exp_f32_e32 v66, v66
	v_exp_f32_e32 v67, v67
	v_exp_f32_e32 v68, v68
	v_exp_f32_e32 v69, v69
	v_exp_f32_e32 v70, v70
	v_exp_f32_e32 v71, v71
	v_exp_f32_e32 v72, v72
	v_exp_f32_e32 v73, v73
	v_exp_f32_e32 v74, v74
	v_exp_f32_e32 v75, v75
	v_exp_f32_e32 v76, v76
	v_exp_f32_e32 v77, v77
	v_exp_f32_e32 v78, v78
	v_exp_f32_e32 v79, v79
	v_add_f32_e32 v190, v80, v81
	v_add_f32_e32 v191, v82, v83
	v_add_f32_e32 v190, v190, v84
	v_add_f32_e32 v191, v191, v85
	v_add_f32_e32 v190, v190, v86
	v_add_f32_e32 v191, v191, v87
	v_add_f32_e32 v190, v190, v88
	v_add_f32_e32 v191, v191, v89
	v_add_f32_e32 v190, v190, v90
	v_add_f32_e32 v191, v191, v91
	v_add_f32_e32 v190, v190, v92
	v_add_f32_e32 v191, v191, v93
	v_add_f32_e32 v190, v190, v94
	v_add_f32_e32 v191, v191, v95
	v_add_f32_e32 v190, v190, v64
	v_add_f32_e32 v191, v191, v65
	v_add_f32_e32 v190, v190, v66
	v_add_f32_e32 v191, v191, v67
	v_add_f32_e32 v190, v190, v68
	v_add_f32_e32 v191, v191, v69
	v_add_f32_e32 v190, v190, v70
	v_add_f32_e32 v191, v191, v71
	v_add_f32_e32 v190, v190, v72
	v_add_f32_e32 v191, v191, v73
	v_add_f32_e32 v190, v190, v74
	v_add_f32_e32 v191, v191, v75
	v_add_f32_e32 v190, v190, v76
	v_add_f32_e32 v191, v191, v77
	v_add_f32_e32 v190, v190, v78
	v_add_f32_e32 v191, v191, v79
	v_add_f32_e32 v190, v190, v191
	v_cvt_pk_bf16_f32 v166, v80, v81
	v_cvt_pk_bf16_f32 v167, v82, v83
	v_cvt_pk_bf16_f32 v168, v84, v85
	v_cvt_pk_bf16_f32 v169, v86, v87
	v_cvt_pk_bf16_f32 v170, v88, v89
	v_cvt_pk_bf16_f32 v171, v90, v91
	v_cvt_pk_bf16_f32 v172, v92, v93
	v_cvt_pk_bf16_f32 v173, v94, v95
	v_cvt_pk_bf16_f32 v176, v64, v65
	v_cvt_pk_bf16_f32 v177, v66, v67
	v_cvt_pk_bf16_f32 v178, v68, v69
	v_cvt_pk_bf16_f32 v179, v70, v71
	v_cvt_pk_bf16_f32 v180, v72, v73
	v_cvt_pk_bf16_f32 v181, v74, v75
	v_cvt_pk_bf16_f32 v182, v76, v77
	v_cvt_pk_bf16_f32 v183, v78, v79
	v_permlane32_swap_b32_e32 v166, v168
	v_permlane32_swap_b32_e32 v167, v169
	v_permlane32_swap_b32_e32 v170, v172
	v_permlane32_swap_b32_e32 v171, v173
	v_permlane32_swap_b32_e32 v176, v178
	v_permlane32_swap_b32_e32 v177, v179
	v_permlane32_swap_b32_e32 v180, v182
	v_permlane32_swap_b32_e32 v181, v183
	v_add_f32_e32 v175, v175, v190
	s_add_u32 s31, s31, 1
	s_cmp_lt_u32 s31, 132
	s_cbranch_scc0 .Lda_skipk_0
	ds_read_b128 v[150:153], v204 offset:16384
	ds_read_b128 v[154:157], v204 offset:24576
	ds_read_b128 v[158:161], v205 offset:16384
	ds_read_b128 v[162:165], v205 offset:24576
	ds_read_b128 v[228:231], v206 offset:16384
	ds_read_b128 v[232:235], v206 offset:24576
	ds_read_b128 v[236:239], v207 offset:16384
	ds_read_b128 v[240:243], v207 offset:24576
.Lda_skipk_0:
	s_barrier
	s_setprio 3
	s_waitcnt vmcnt(4)
	ds_write_b128 v197, v[186:189] offset:49152
	ds_write_b128 v197, v[220:223] offset:57344
	ds_write_b128 v185, v[246:249] offset:49152
	ds_write_b128 v185, v[200:203] offset:57344
	s_waitcnt lgkmcnt(10)
	v_mfma_f32_32x32x16_bf16 v[80:95], v[150:153], v[130:133], 0
	v_mfma_f32_32x32x16_bf16 v[64:79], v[154:157], v[130:133], 0
	global_load_dwordx4 v[186:189], v184, s[16:17]
	global_load_dwordx4 v[220:223], v184, s[2:3]
	global_load_dwordx4 v[246:249], v184, s[14:15]
	global_load_dwordx4 v[200:203], v184, s[10:11]
	s_add_u32 s16, s16, 0x60000
	s_addc_u32 s17, s17, 0
	s_add_u32 s2, s2, 0x60000
	s_addc_u32 s3, s3, 0
	s_add_u32 s14, s14, 0x60000
	s_addc_u32 s15, s15, 0
	s_add_u32 s10, s10, 0x60000
	s_addc_u32 s11, s11, 0
	ds_read_b128 v[150:153], v208 offset:16384
	ds_read_b128 v[154:157], v208 offset:24576
	s_waitcnt lgkmcnt(10)
	v_mfma_f32_32x32x16_bf16 v[80:95], v[158:161], v[126:129], v[80:95]
	v_mfma_f32_32x32x16_bf16 v[64:79], v[162:165], v[126:129], v[64:79]
	ds_read_b128 v[158:161], v209 offset:16384
	ds_read_b128 v[162:165], v209 offset:24576
	s_waitcnt lgkmcnt(10)
	v_mfma_f32_32x32x16_bf16 v[80:95], v[228:231], v[122:125], v[80:95]
	v_mfma_f32_32x32x16_bf16 v[64:79], v[232:235], v[122:125], v[64:79]
	ds_read_b128 v[228:231], v210 offset:16384
	ds_read_b128 v[232:235], v210 offset:24576
	s_waitcnt lgkmcnt(10)
	v_mfma_f32_32x32x16_bf16 v[80:95], v[236:239], v[118:121], v[80:95]
	v_mfma_f32_32x32x16_bf16 v[64:79], v[240:243], v[118:121], v[64:79]
	ds_read_b128 v[236:239], v211 offset:16384
	ds_read_b128 v[240:243], v211 offset:24576
	s_waitcnt lgkmcnt(6)
	v_mfma_f32_32x32x16_bf16 v[80:95], v[150:153], v[114:117], v[80:95]
	v_mfma_f32_32x32x16_bf16 v[64:79], v[154:157], v[114:117], v[64:79]
	ds_read_b64_tr_b16 v[150:151], v196 offset:0
	ds_read_b64_tr_b16 v[152:153], v196 offset:2048
	ds_read_b64_tr_b16 v[154:155], v196 offset:4096
	ds_read_b64_tr_b16 v[156:157], v196 offset:6144
	s_waitcnt lgkmcnt(8)
	v_mfma_f32_32x32x16_bf16 v[80:95], v[158:161], v[110:113], v[80:95]
	v_mfma_f32_32x32x16_bf16 v[64:79], v[162:165], v[110:113], v[64:79]
	ds_read_b64_tr_b16 v[158:159], v196 offset:8192
	ds_read_b64_tr_b16 v[160:161], v196 offset:10240
	ds_read_b64_tr_b16 v[162:163], v196 offset:12288
	ds_read_b64_tr_b16 v[164:165], v196 offset:14336
	s_waitcnt lgkmcnt(10)
; #define SBAR() __builtin_amdgcn_sched_barrier(0)
; __device__ __forceinline__ void partialSM(f32x16& p0, f32x16& p1, float& m_reg, float& mn, float& alpha) {
;   constexpr float C = SCALE * 1.4426950408889634f;
;   float pmax = p0[0];
; #pragma unroll
;   for (int r = 1; r < 16; ++r) pmax = fmaxf(pmax, p0[r]);
; #pragma unroll
;   for (int r = 0; r < 16; ++r) pmax = fmaxf(pmax, p1[r]);
;   { auto rr = __builtin_amdgcn_permlane32_swap(__float_as_uint(pmax), __float_as_uint(pmax), false, false);
;     pmax = fmaxf(__uint_as_float(rr[0]), __uint_as_float(rr[1])); }
;   if (__builtin_expect(__all(pmax - m_reg <= THR / SCALE), 1)) { mn = m_reg; alpha = 1.f; }
;   else { mn = fmaxf(m_reg, pmax); alpha = __builtin_amdgcn_exp2f((m_reg - mn) * C); m_reg = mn; }
; template <int D0> __device__ __forceinline__ void pv_one(f32x16& od, int vb, bf16x8 pa0, bf16x8 pa1, bf16x8 pa2, bf16x8 pa3) {
;   const s16x4 l0 = tr_read<v_rd_off(D0, 0, 0)>(vb), h0 = tr_read<v_rd_off(D0, 0, 1)>(vb), l1 = tr_read<v_rd_off(D0, 1, 0)>(vb), h1 = tr_read<v_rd_off(D0, 1, 1)>(vb);
;   const s16x4 l2 = tr_read<v_rd_off(D0, 2, 0)>(vb), h2 = tr_read<v_rd_off(D0, 2, 1)>(vb), l3 = tr_read<v_rd_off(D0, 3, 0)>(vb), h3 = tr_read<v_rd_off(D0, 3, 1)>(vb);
;   asm volatile("s_waitcnt lgkmcnt(0)" ::: "memory"); SBAR();
;     ...
;   od = __builtin_amdgcn_mfma_f32_32x32x16_bf16(pa0, PK(l0, h0), od, 0, 0, 0);
;   od = __builtin_amdgcn_mfma_f32_32x32x16_bf16(pa1, PK(l1, h1), od, 0, 0, 0);
;   od = __builtin_amdgcn_mfma_f32_32x32x16_bf16(pa2, PK(l2, h2), od, 0, 0, 0);
;   od = __builtin_amdgcn_mfma_f32_32x32x16_bf16(pa3, PK(l3, h3), od, 0, 0, 0);
;     ...
; }
; __device__ __forceinline__ void pv_d0(f32x16* o, int vb, bf16x8 pa0, bf16x8 pa1, bf16x8 pa2, bf16x8 pa3) {
;   pv_one<0>(o[0], vb, pa0, pa1, pa2, pa3); pv_one<1>(o[1], vb, pa0, pa1, pa2, pa3); pv_one<2>(o[2], vb, pa0, pa1, pa2, pa3); pv_one<3>(o[3], vb, pa0, pa1, pa2, pa3);
	v_mfma_f32_32x32x16_bf16 v[80:95], v[228:231], v[106:109], v[80:95]
	v_mfma_f32_32x32x16_bf16 v[64:79], v[232:235], v[106:109], v[64:79]
	ds_read_b64_tr_b16 v[228:229], v196 offset:512
	ds_read_b64_tr_b16 v[230:231], v196 offset:2560
	ds_read_b64_tr_b16 v[232:233], v196 offset:4608
	ds_read_b64_tr_b16 v[234:235], v196 offset:6656
	s_waitcnt lgkmcnt(12)
	v_mfma_f32_32x32x16_bf16 v[80:95], v[236:239], v[102:105], v[80:95]
	v_mfma_f32_32x32x16_bf16 v[64:79], v[240:243], v[102:105], v[64:79]
	ds_read_b64_tr_b16 v[236:237], v196 offset:8704
	ds_read_b64_tr_b16 v[238:239], v196 offset:10752
	s_waitcnt lgkmcnt(12)
	v_mfma_f32_32x32x16_bf16 v[0:15], v[166:169], v[150:153], v[0:15]
	ds_read_b64_tr_b16 v[240:241], v196 offset:12800
	ds_read_b64_tr_b16 v[242:243], v196 offset:14848
	s_waitcnt lgkmcnt(12)
	v_mfma_f32_32x32x16_bf16 v[0:15], v[170:173], v[154:157], v[0:15]
	ds_read_b64_tr_b16 v[150:151], v196 offset:1024
	ds_read_b64_tr_b16 v[152:153], v196 offset:3072
	s_waitcnt lgkmcnt(12)
	v_mfma_f32_32x32x16_bf16 v[0:15], v[176:179], v[158:161], v[0:15]
	ds_read_b64_tr_b16 v[154:155], v196 offset:5120
	ds_read_b64_tr_b16 v[156:157], v196 offset:7168
	s_waitcnt lgkmcnt(12)
	v_mfma_f32_32x32x16_bf16 v[0:15], v[180:183], v[162:165], v[0:15]
	ds_read_b64_tr_b16 v[158:159], v196 offset:9216
	ds_read_b64_tr_b16 v[160:161], v196 offset:11264
	s_waitcnt lgkmcnt(12)
	v_mfma_f32_32x32x16_bf16 v[48:63], v[166:169], v[228:231], v[48:63]
	ds_read_b64_tr_b16 v[162:163], v196 offset:13312
	ds_read_b64_tr_b16 v[164:165], v196 offset:15360
	s_waitcnt lgkmcnt(12)
	v_mfma_f32_32x32x16_bf16 v[48:63], v[170:173], v[232:235], v[48:63]
	ds_read_b64_tr_b16 v[228:229], v196 offset:1536
	ds_read_b64_tr_b16 v[230:231], v196 offset:3584
	s_waitcnt lgkmcnt(12)
	v_mfma_f32_32x32x16_bf16 v[48:63], v[176:179], v[236:239], v[48:63]
	ds_read_b64_tr_b16 v[232:233], v196 offset:5632
	ds_read_b64_tr_b16 v[234:235], v196 offset:7680
	s_waitcnt lgkmcnt(12)
	v_mfma_f32_32x32x16_bf16 v[48:63], v[180:183], v[240:243], v[48:63]
	ds_read_b64_tr_b16 v[236:237], v196 offset:9728
	ds_read_b64_tr_b16 v[238:239], v196 offset:11776
	s_waitcnt lgkmcnt(12)
	v_mfma_f32_32x32x16_bf16 v[32:47], v[166:169], v[150:153], v[32:47]
	ds_read_b64_tr_b16 v[240:241], v196 offset:13824
	ds_read_b64_tr_b16 v[242:243], v196 offset:15872
	s_waitcnt lgkmcnt(12)
	v_mfma_f32_32x32x16_bf16 v[32:47], v[170:173], v[154:157], v[32:47]
	s_waitcnt lgkmcnt(10)
	v_mfma_f32_32x32x16_bf16 v[32:47], v[176:179], v[158:161], v[32:47]
	s_waitcnt lgkmcnt(8)
	v_mfma_f32_32x32x16_bf16 v[32:47], v[180:183], v[162:165], v[32:47]
	s_waitcnt lgkmcnt(6)
	v_mfma_f32_32x32x16_bf16 v[16:31], v[166:169], v[228:231], v[16:31]
	s_waitcnt lgkmcnt(4)
	v_mfma_f32_32x32x16_bf16 v[16:31], v[170:173], v[232:235], v[16:31]
	s_waitcnt lgkmcnt(2)
	v_mfma_f32_32x32x16_bf16 v[16:31], v[176:179], v[236:239], v[16:31]
	s_waitcnt lgkmcnt(0)
	v_mfma_f32_32x32x16_bf16 v[16:31], v[180:183], v[240:243], v[16:31]
	s_setprio 0
	s_barrier
	v_max3_f32 v190, v80, v81, v82
	v_max3_f32 v191, v64, v65, v66
	v_max3_f32 v190, v190, v83, v84
	v_max3_f32 v191, v191, v67, v68
	v_max3_f32 v190, v190, v85, v86
	v_max3_f32 v191, v191, v69, v70
	v_max3_f32 v190, v190, v87, v88
	v_max3_f32 v191, v191, v71, v72
	v_max3_f32 v190, v190, v89, v90
	v_max3_f32 v191, v191, v73, v74
	v_max3_f32 v190, v190, v91, v92
	v_max3_f32 v191, v191, v75, v76
	v_max3_f32 v190, v190, v93, v94
	v_max3_f32 v191, v191, v77, v78
	v_max3_f32 v190, v190, v95, v79
	v_max_f32_e32 v190, v190, v191
	v_sub_f32_e32 v215, v190, v174
	v_cmp_ge_f32_e32 vcc, s86, v215
	s_nop 0
	s_cmp_eq_u64 vcc, exec
	s_cbranch_scc1 .Lda_common_1
	v_mov_b32_e32 v191, v190
	s_nop 1
	v_permlane32_swap_b32_e32 v190, v191
	s_nop 0
	v_max_f32_e32 v212, v190, v191
	v_max_f32_e32 v191, v174, v212
	v_sub_f32_e32 v215, v174, v191
	v_mul_f32_e32 v215, s92, v215
	v_exp_f32_e32 v213, v215
	v_mov_b32_e32 v174, v191
	v_mul_f32_e32 v214, 0xbe0293ee, v174
	v_mul_f32_e32 v175, v175, v213
	s_and_saveexec_b64 s[12:13], s[40:41]
	ds_write_b32 v199, v213 offset:128
	s_or_b64 exec, exec, s[12:13]
	s_waitcnt lgkmcnt(0)
	v_add_u32_e32 v215, v99, v96
	ds_read_b128 v[228:231], v215 offset:128
	ds_read_b128 v[232:235], v215 offset:160
	ds_read_b128 v[236:239], v215 offset:192
	ds_read_b128 v[240:243], v215 offset:224
	s_waitcnt lgkmcnt(0)
	v_pk_mul_f32 v[0:1], v[0:1], v[228:229]
	v_pk_mul_f32 v[2:3], v[2:3], v[230:231]
	v_pk_mul_f32 v[4:5], v[4:5], v[232:233]
	v_pk_mul_f32 v[6:7], v[6:7], v[234:235]
	v_pk_mul_f32 v[8:9], v[8:9], v[236:237]
	v_pk_mul_f32 v[10:11], v[10:11], v[238:239]
	v_pk_mul_f32 v[12:13], v[12:13], v[240:241]
	v_pk_mul_f32 v[14:15], v[14:15], v[242:243]
	v_pk_mul_f32 v[48:49], v[48:49], v[228:229]
	v_pk_mul_f32 v[50:51], v[50:51], v[230:231]
	v_pk_mul_f32 v[52:53], v[52:53], v[232:233]
	v_pk_mul_f32 v[54:55], v[54:55], v[234:235]
	v_pk_mul_f32 v[56:57], v[56:57], v[236:237]
	v_pk_mul_f32 v[58:59], v[58:59], v[238:239]
	v_pk_mul_f32 v[60:61], v[60:61], v[240:241]
	v_pk_mul_f32 v[62:63], v[62:63], v[242:243]
	v_pk_mul_f32 v[32:33], v[32:33], v[228:229]
	v_pk_mul_f32 v[34:35], v[34:35], v[230:231]
	v_pk_mul_f32 v[36:37], v[36:37], v[232:233]
	v_pk_mul_f32 v[38:39], v[38:39], v[234:235]
	v_pk_mul_f32 v[40:41], v[40:41], v[236:237]
	v_pk_mul_f32 v[42:43], v[42:43], v[238:239]
	v_pk_mul_f32 v[44:45], v[44:45], v[240:241]
	v_pk_mul_f32 v[46:47], v[46:47], v[242:243]
	v_pk_mul_f32 v[16:17], v[16:17], v[228:229]
	v_pk_mul_f32 v[18:19], v[18:19], v[230:231]
	v_pk_mul_f32 v[20:21], v[20:21], v[232:233]
	v_pk_mul_f32 v[22:23], v[22:23], v[234:235]
	v_pk_mul_f32 v[24:25], v[24:25], v[236:237]
	v_pk_mul_f32 v[26:27], v[26:27], v[238:239]
	v_pk_mul_f32 v[28:29], v[28:29], v[240:241]
	v_pk_mul_f32 v[30:31], v[30:31], v[242:243]

; __device__ __forceinline__ void finishSM(f32x16& p0, f32x16& p1, float alpha, float& l_reg, bf16x8& pa0, bf16x8& pa1, bf16x8& pa2, bf16x8& pa3) {
; #pragma unroll
;   for (int r = 0; r < 16; ++r) p1[r] = __builtin_amdgcn_exp2f(p1[r]);
;   float ps = 0;
; #pragma unroll
;   for (int r = 0; r < 16; ++r) ps += p0[r];
; #pragma unroll
;   for (int r = 0; r < 16; ++r) ps += p1[r];
;   { auto rr = __builtin_amdgcn_permlane32_swap(__float_as_uint(ps), __float_as_uint(ps), false, false);
;     ps = __uint_as_float(rr[0]) + __uint_as_float(rr[1]); }
;   l_reg = l_reg * alpha + ps;
;     ...
;   PK4(p0, 0, pa0); PK4(p0, 8, pa1); PK4(p1, 0, pa2); PK4(p1, 8, pa3);
;     ...
; }
; __device__ __forceinline__ void qkt(f32x16& p0, f32x16& p1, const bf16_t* Ks, const bf16x8* qr, int r32, int hi) {
;   p0 = f32x16{}; p1 = f32x16{};
; #pragma unroll
;   for (int d0 = 0; d0 < 8; ++d0) { int cb = (d0 * 16 + hi * 8) * 2;
;     bf16x8 b0 = *reinterpret_cast<const bf16x8*>((const char*)Ks + KSWZ(r32, cb));
;     bf16x8 b1 = *reinterpret_cast<const bf16x8*>((const char*)Ks + KSWZ(32 + r32, cb));
;     p0 = __builtin_amdgcn_mfma_f32_32x32x16_bf16(b0, qr[d0], p0, 0, 0, 0);
;     p1 = __builtin_amdgcn_mfma_f32_32x32x16_bf16(b1, qr[d0], p1, 0, 0, 0); }
; }
.Lda_noresc_1:
	v_exp_f32_e32 v80, v80
	v_exp_f32_e32 v81, v81
	v_exp_f32_e32 v82, v82
	v_exp_f32_e32 v83, v83
	v_exp_f32_e32 v84, v84
	v_exp_f32_e32 v85, v85
	v_exp_f32_e32 v86, v86
	v_exp_f32_e32 v87, v87
	v_exp_f32_e32 v88, v88
	v_exp_f32_e32 v89, v89
	v_exp_f32_e32 v90, v90
	v_exp_f32_e32 v91, v91
	v_exp_f32_e32 v92, v92
	v_exp_f32_e32 v93, v93
	v_exp_f32_e32 v94, v94
	v_exp_f32_e32 v95, v95
	v_exp_f32_e32 v64, v64
	v_exp_f32_e32 v65, v65
	v_exp_f32_e32 v66, v66
	v_exp_f32_e32 v67, v67
	v_exp_f32_e32 v68, v68
	v_exp_f32_e32 v69, v69
	v_exp_f32_e32 v70, v70
	v_exp_f32_e32 v71, v71
	v_exp_f32_e32 v72, v72
	v_exp_f32_e32 v73, v73
	v_exp_f32_e32 v74, v74
	v_exp_f32_e32 v75, v75
	v_exp_f32_e32 v76, v76
	v_exp_f32_e32 v77, v77
	v_exp_f32_e32 v78, v78
	v_exp_f32_e32 v79, v79
	v_add_f32_e32 v190, v80, v81
	v_add_f32_e32 v191, v82, v83
	v_add_f32_e32 v190, v190, v84
	v_add_f32_e32 v191, v191, v85
	v_add_f32_e32 v190, v190, v86
	v_add_f32_e32 v191, v191, v87
	v_add_f32_e32 v190, v190, v88
	v_add_f32_e32 v191, v191, v89
	v_add_f32_e32 v190, v190, v90
	v_add_f32_e32 v191, v191, v91
	v_add_f32_e32 v190, v190, v92
	v_add_f32_e32 v191, v191, v93
	v_add_f32_e32 v190, v190, v94
	v_add_f32_e32 v191, v191, v95
	v_add_f32_e32 v190, v190, v64
	v_add_f32_e32 v191, v191, v65
	v_add_f32_e32 v190, v190, v66
	v_add_f32_e32 v191, v191, v67
	v_add_f32_e32 v190, v190, v68
	v_add_f32_e32 v191, v191, v69
	v_add_f32_e32 v190, v190, v70
	v_add_f32_e32 v191, v191, v71
	v_add_f32_e32 v190, v190, v72
	v_add_f32_e32 v191, v191, v73
	v_add_f32_e32 v190, v190, v74
	v_add_f32_e32 v191, v191, v75
	v_add_f32_e32 v190, v190, v76
	v_add_f32_e32 v191, v191, v77
	v_add_f32_e32 v190, v190, v78
	v_add_f32_e32 v191, v191, v79
	v_add_f32_e32 v190, v190, v191
	v_cvt_pk_bf16_f32 v166, v80, v81
	v_cvt_pk_bf16_f32 v167, v82, v83
	v_cvt_pk_bf16_f32 v168, v84, v85
	v_cvt_pk_bf16_f32 v169, v86, v87
	v_cvt_pk_bf16_f32 v170, v88, v89
	v_cvt_pk_bf16_f32 v171, v90, v91
	v_cvt_pk_bf16_f32 v172, v92, v93
	v_cvt_pk_bf16_f32 v173, v94, v95
	v_cvt_pk_bf16_f32 v176, v64, v65
	v_cvt_pk_bf16_f32 v177, v66, v67
	v_cvt_pk_bf16_f32 v178, v68, v69
	v_cvt_pk_bf16_f32 v179, v70, v71
	v_cvt_pk_bf16_f32 v180, v72, v73
	v_cvt_pk_bf16_f32 v181, v74, v75
	v_cvt_pk_bf16_f32 v182, v76, v77
	v_cvt_pk_bf16_f32 v183, v78, v79
	v_permlane32_swap_b32_e32 v166, v168
	v_permlane32_swap_b32_e32 v167, v169
	v_permlane32_swap_b32_e32 v170, v172
	v_permlane32_swap_b32_e32 v171, v173
	v_permlane32_swap_b32_e32 v176, v178
	v_permlane32_swap_b32_e32 v177, v179
	v_permlane32_swap_b32_e32 v180, v182
	v_permlane32_swap_b32_e32 v181, v183
	v_add_f32_e32 v175, v175, v190
	s_add_u32 s31, s31, 1
	s_cmp_lt_u32 s31, 132
	s_cbranch_scc0 .Lda_skipk_1
	ds_read_b128 v[150:153], v204 offset:32768
	ds_read_b128 v[154:157], v204 offset:40960
	ds_read_b128 v[158:161], v205 offset:32768
	ds_read_b128 v[162:165], v205 offset:40960
	ds_read_b128 v[228:231], v206 offset:32768
	ds_read_b128 v[232:235], v206 offset:40960
	ds_read_b128 v[236:239], v207 offset:32768
	ds_read_b128 v[240:243], v207 offset:40960
.Lda_skipk_1:
	s_barrier
	s_setprio 3
	s_waitcnt vmcnt(4)
	ds_write_b128 v197, v[134:137] offset:0
	ds_write_b128 v197, v[138:141] offset:8192
	ds_write_b128 v185, v[142:145] offset:0
	ds_write_b128 v185, v[146:149] offset:8192
	s_waitcnt lgkmcnt(10)
	v_mfma_f32_32x32x16_bf16 v[80:95], v[150:153], v[130:133], 0
	v_mfma_f32_32x32x16_bf16 v[64:79], v[154:157], v[130:133], 0
	global_load_dwordx4 v[134:137], v184, s[16:17]
	global_load_dwordx4 v[138:141], v184, s[2:3]
	global_load_dwordx4 v[142:145], v184, s[14:15]
	global_load_dwordx4 v[146:149], v184, s[10:11]
	s_add_u32 s16, s16, 0x60000
	s_addc_u32 s17, s17, 0
	s_add_u32 s2, s2, 0x60000
	s_addc_u32 s3, s3, 0
	s_add_u32 s14, s14, 0x60000
	s_addc_u32 s15, s15, 0
	s_add_u32 s10, s10, 0x60000
	s_addc_u32 s11, s11, 0
	ds_read_b128 v[150:153], v208 offset:32768
	ds_read_b128 v[154:157], v208 offset:40960
	s_waitcnt lgkmcnt(10)
	v_mfma_f32_32x32x16_bf16 v[80:95], v[158:161], v[126:129], v[80:95]
	v_mfma_f32_32x32x16_bf16 v[64:79], v[162:165], v[126:129], v[64:79]
	ds_read_b128 v[158:161], v209 offset:32768
	ds_read_b128 v[162:165], v209 offset:40960
	s_waitcnt lgkmcnt(10)
	v_mfma_f32_32x32x16_bf16 v[80:95], v[228:231], v[122:125], v[80:95]
	v_mfma_f32_32x32x16_bf16 v[64:79], v[232:235], v[122:125], v[64:79]
	ds_read_b128 v[228:231], v210 offset:32768
	ds_read_b128 v[232:235], v210 offset:40960
	s_waitcnt lgkmcnt(10)
	v_mfma_f32_32x32x16_bf16 v[80:95], v[236:239], v[118:121], v[80:95]
	v_mfma_f32_32x32x16_bf16 v[64:79], v[240:243], v[118:121], v[64:79]
	ds_read_b128 v[236:239], v211 offset:32768
	ds_read_b128 v[240:243], v211 offset:40960
	s_waitcnt lgkmcnt(6)
	v_mfma_f32_32x32x16_bf16 v[80:95], v[150:153], v[114:117], v[80:95]
	v_mfma_f32_32x32x16_bf16 v[64:79], v[154:157], v[114:117], v[64:79]
	ds_read_b64_tr_b16 v[150:151], v196 offset:16384
	ds_read_b64_tr_b16 v[152:153], v196 offset:18432
	ds_read_b64_tr_b16 v[154:155], v196 offset:20480
	ds_read_b64_tr_b16 v[156:157], v196 offset:22528
	s_waitcnt lgkmcnt(8)
	v_mfma_f32_32x32x16_bf16 v[80:95], v[158:161], v[110:113], v[80:95]
	v_mfma_f32_32x32x16_bf16 v[64:79], v[162:165], v[110:113], v[64:79]
	ds_read_b64_tr_b16 v[158:159], v196 offset:24576
	ds_read_b64_tr_b16 v[160:161], v196 offset:26624
	ds_read_b64_tr_b16 v[162:163], v196 offset:28672
	ds_read_b64_tr_b16 v[164:165], v196 offset:30720
	s_waitcnt lgkmcnt(10)
; #define SBAR() __builtin_amdgcn_sched_barrier(0)
; __device__ __forceinline__ void partialSM(f32x16& p0, f32x16& p1, float& m_reg, float& mn, float& alpha) {
;   constexpr float C = SCALE * 1.4426950408889634f;
;   float pmax = p0[0];
; #pragma unroll
;   for (int r = 1; r < 16; ++r) pmax = fmaxf(pmax, p0[r]);
; #pragma unroll
;   for (int r = 0; r < 16; ++r) pmax = fmaxf(pmax, p1[r]);
;   { auto rr = __builtin_amdgcn_permlane32_swap(__float_as_uint(pmax), __float_as_uint(pmax), false, false);
;     pmax = fmaxf(__uint_as_float(rr[0]), __uint_as_float(rr[1])); }
;   if (__builtin_expect(__all(pmax - m_reg <= THR / SCALE), 1)) { mn = m_reg; alpha = 1.f; }
;   else { mn = fmaxf(m_reg, pmax); alpha = __builtin_amdgcn_exp2f((m_reg - mn) * C); m_reg = mn; }
; template <int D0> __device__ __forceinline__ void pv_one(f32x16& od, int vb, bf16x8 pa0, bf16x8 pa1, bf16x8 pa2, bf16x8 pa3) {
;   const s16x4 l0 = tr_read<v_rd_off(D0, 0, 0)>(vb), h0 = tr_read<v_rd_off(D0, 0, 1)>(vb), l1 = tr_read<v_rd_off(D0, 1, 0)>(vb), h1 = tr_read<v_rd_off(D0, 1, 1)>(vb);
;   const s16x4 l2 = tr_read<v_rd_off(D0, 2, 0)>(vb), h2 = tr_read<v_rd_off(D0, 2, 1)>(vb), l3 = tr_read<v_rd_off(D0, 3, 0)>(vb), h3 = tr_read<v_rd_off(D0, 3, 1)>(vb);
;   asm volatile("s_waitcnt lgkmcnt(0)" ::: "memory"); SBAR();
;     ...
;   od = __builtin_amdgcn_mfma_f32_32x32x16_bf16(pa0, PK(l0, h0), od, 0, 0, 0);
;   od = __builtin_amdgcn_mfma_f32_32x32x16_bf16(pa1, PK(l1, h1), od, 0, 0, 0);
;   od = __builtin_amdgcn_mfma_f32_32x32x16_bf16(pa2, PK(l2, h2), od, 0, 0, 0);
;   od = __builtin_amdgcn_mfma_f32_32x32x16_bf16(pa3, PK(l3, h3), od, 0, 0, 0);
;     ...
; }
; __device__ __forceinline__ void pv_d0(f32x16* o, int vb, bf16x8 pa0, bf16x8 pa1, bf16x8 pa2, bf16x8 pa3) {
;   pv_one<0>(o[0], vb, pa0, pa1, pa2, pa3); pv_one<1>(o[1], vb, pa0, pa1, pa2, pa3); pv_one<2>(o[2], vb, pa0, pa1, pa2, pa3); pv_one<3>(o[3], vb, pa0, pa1, pa2, pa3);
	v_mfma_f32_32x32x16_bf16 v[80:95], v[228:231], v[106:109], v[80:95]
	v_mfma_f32_32x32x16_bf16 v[64:79], v[232:235], v[106:109], v[64:79]
	ds_read_b64_tr_b16 v[228:229], v196 offset:16896
	ds_read_b64_tr_b16 v[230:231], v196 offset:18944
	ds_read_b64_tr_b16 v[232:233], v196 offset:20992
	ds_read_b64_tr_b16 v[234:235], v196 offset:23040
	s_waitcnt lgkmcnt(12)
	v_mfma_f32_32x32x16_bf16 v[80:95], v[236:239], v[102:105], v[80:95]
	v_mfma_f32_32x32x16_bf16 v[64:79], v[240:243], v[102:105], v[64:79]
	ds_read_b64_tr_b16 v[236:237], v196 offset:25088
	ds_read_b64_tr_b16 v[238:239], v196 offset:27136
	s_waitcnt lgkmcnt(12)
	v_mfma_f32_32x32x16_bf16 v[0:15], v[166:169], v[150:153], v[0:15]
	ds_read_b64_tr_b16 v[240:241], v196 offset:29184
	ds_read_b64_tr_b16 v[242:243], v196 offset:31232
	s_waitcnt lgkmcnt(12)
	v_mfma_f32_32x32x16_bf16 v[0:15], v[170:173], v[154:157], v[0:15]
	ds_read_b64_tr_b16 v[150:151], v196 offset:17408
	ds_read_b64_tr_b16 v[152:153], v196 offset:19456
	s_waitcnt lgkmcnt(12)
	v_mfma_f32_32x32x16_bf16 v[0:15], v[176:179], v[158:161], v[0:15]
	ds_read_b64_tr_b16 v[154:155], v196 offset:21504
	ds_read_b64_tr_b16 v[156:157], v196 offset:23552
	s_waitcnt lgkmcnt(12)
	v_mfma_f32_32x32x16_bf16 v[0:15], v[180:183], v[162:165], v[0:15]
	ds_read_b64_tr_b16 v[158:159], v196 offset:25600
	ds_read_b64_tr_b16 v[160:161], v196 offset:27648
	s_waitcnt lgkmcnt(12)
	v_mfma_f32_32x32x16_bf16 v[48:63], v[166:169], v[228:231], v[48:63]
	ds_read_b64_tr_b16 v[162:163], v196 offset:29696
	ds_read_b64_tr_b16 v[164:165], v196 offset:31744
	s_waitcnt lgkmcnt(12)
	v_mfma_f32_32x32x16_bf16 v[48:63], v[170:173], v[232:235], v[48:63]
	ds_read_b64_tr_b16 v[228:229], v196 offset:17920
	ds_read_b64_tr_b16 v[230:231], v196 offset:19968
	s_waitcnt lgkmcnt(12)
	v_mfma_f32_32x32x16_bf16 v[48:63], v[176:179], v[236:239], v[48:63]
	ds_read_b64_tr_b16 v[232:233], v196 offset:22016
	ds_read_b64_tr_b16 v[234:235], v196 offset:24064
	s_waitcnt lgkmcnt(12)
	v_mfma_f32_32x32x16_bf16 v[48:63], v[180:183], v[240:243], v[48:63]
	ds_read_b64_tr_b16 v[236:237], v196 offset:26112
	ds_read_b64_tr_b16 v[238:239], v196 offset:28160
	s_waitcnt lgkmcnt(12)
	v_mfma_f32_32x32x16_bf16 v[32:47], v[166:169], v[150:153], v[32:47]
	ds_read_b64_tr_b16 v[240:241], v196 offset:30208
	ds_read_b64_tr_b16 v[242:243], v196 offset:32256
	s_waitcnt lgkmcnt(12)
	v_mfma_f32_32x32x16_bf16 v[32:47], v[170:173], v[154:157], v[32:47]
	s_waitcnt lgkmcnt(10)
	v_mfma_f32_32x32x16_bf16 v[32:47], v[176:179], v[158:161], v[32:47]
	s_waitcnt lgkmcnt(8)
	v_mfma_f32_32x32x16_bf16 v[32:47], v[180:183], v[162:165], v[32:47]
	s_waitcnt lgkmcnt(6)
	v_mfma_f32_32x32x16_bf16 v[16:31], v[166:169], v[228:231], v[16:31]
	s_waitcnt lgkmcnt(4)
	v_mfma_f32_32x32x16_bf16 v[16:31], v[170:173], v[232:235], v[16:31]
	s_waitcnt lgkmcnt(2)
	v_mfma_f32_32x32x16_bf16 v[16:31], v[176:179], v[236:239], v[16:31]
	s_waitcnt lgkmcnt(0)
	v_mfma_f32_32x32x16_bf16 v[16:31], v[180:183], v[240:243], v[16:31]
	s_setprio 0
	s_barrier
	v_max3_f32 v190, v80, v81, v82
	v_max3_f32 v191, v64, v65, v66
	v_max3_f32 v190, v190, v83, v84
	v_max3_f32 v191, v191, v67, v68
	v_max3_f32 v190, v190, v85, v86
	v_max3_f32 v191, v191, v69, v70
	v_max3_f32 v190, v190, v87, v88
	v_max3_f32 v191, v191, v71, v72
	v_max3_f32 v190, v190, v89, v90
	v_max3_f32 v191, v191, v73, v74
	v_max3_f32 v190, v190, v91, v92
	v_max3_f32 v191, v191, v75, v76
	v_max3_f32 v190, v190, v93, v94
	v_max3_f32 v191, v191, v77, v78
	v_max3_f32 v190, v190, v95, v79
	v_max_f32_e32 v190, v190, v191
	v_sub_f32_e32 v215, v190, v174
	v_cmp_ge_f32_e32 vcc, s86, v215
	s_nop 0
	s_cmp_eq_u64 vcc, exec
	s_cbranch_scc1 .Lda_common_2
	v_mov_b32_e32 v191, v190
	s_nop 1
	v_permlane32_swap_b32_e32 v190, v191
	s_nop 0
	v_max_f32_e32 v212, v190, v191
	v_max_f32_e32 v191, v174, v212
	v_sub_f32_e32 v215, v174, v191
	v_mul_f32_e32 v215, s92, v215
	v_exp_f32_e32 v213, v215
	v_mov_b32_e32 v174, v191
	v_mul_f32_e32 v214, 0xbe0293ee, v174
	v_mul_f32_e32 v175, v175, v213
	s_and_saveexec_b64 s[12:13], s[40:41]
	ds_write_b32 v199, v213 offset:128
	s_or_b64 exec, exec, s[12:13]
	s_waitcnt lgkmcnt(0)
	v_add_u32_e32 v215, v99, v96
	ds_read_b128 v[228:231], v215 offset:128
	ds_read_b128 v[232:235], v215 offset:160
	ds_read_b128 v[236:239], v215 offset:192
	ds_read_b128 v[240:243], v215 offset:224
	s_waitcnt lgkmcnt(0)
	v_pk_mul_f32 v[0:1], v[0:1], v[228:229]
	v_pk_mul_f32 v[2:3], v[2:3], v[230:231]
	v_pk_mul_f32 v[4:5], v[4:5], v[232:233]
	v_pk_mul_f32 v[6:7], v[6:7], v[234:235]
	v_pk_mul_f32 v[8:9], v[8:9], v[236:237]
	v_pk_mul_f32 v[10:11], v[10:11], v[238:239]
	v_pk_mul_f32 v[12:13], v[12:13], v[240:241]
	v_pk_mul_f32 v[14:15], v[14:15], v[242:243]
	v_pk_mul_f32 v[48:49], v[48:49], v[228:229]
	v_pk_mul_f32 v[50:51], v[50:51], v[230:231]
	v_pk_mul_f32 v[52:53], v[52:53], v[232:233]
	v_pk_mul_f32 v[54:55], v[54:55], v[234:235]
	v_pk_mul_f32 v[56:57], v[56:57], v[236:237]
	v_pk_mul_f32 v[58:59], v[58:59], v[238:239]
	v_pk_mul_f32 v[60:61], v[60:61], v[240:241]
	v_pk_mul_f32 v[62:63], v[62:63], v[242:243]
	v_pk_mul_f32 v[32:33], v[32:33], v[228:229]
	v_pk_mul_f32 v[34:35], v[34:35], v[230:231]
	v_pk_mul_f32 v[36:37], v[36:37], v[232:233]
	v_pk_mul_f32 v[38:39], v[38:39], v[234:235]
	v_pk_mul_f32 v[40:41], v[40:41], v[236:237]
	v_pk_mul_f32 v[42:43], v[42:43], v[238:239]
	v_pk_mul_f32 v[44:45], v[44:45], v[240:241]
	v_pk_mul_f32 v[46:47], v[46:47], v[242:243]
	v_pk_mul_f32 v[16:17], v[16:17], v[228:229]
	v_pk_mul_f32 v[18:19], v[18:19], v[230:231]
	v_pk_mul_f32 v[20:21], v[20:21], v[232:233]
	v_pk_mul_f32 v[22:23], v[22:23], v[234:235]
	v_pk_mul_f32 v[24:25], v[24:25], v[236:237]
	v_pk_mul_f32 v[26:27], v[26:27], v[238:239]
	v_pk_mul_f32 v[28:29], v[28:29], v[240:241]
	v_pk_mul_f32 v[30:31], v[30:31], v[242:243]

; __device__ __forceinline__ void finishSM(f32x16& p0, f32x16& p1, float alpha, float& l_reg, bf16x8& pa0, bf16x8& pa1, bf16x8& pa2, bf16x8& pa3) {
; #pragma unroll
;   for (int r = 0; r < 16; ++r) p1[r] = __builtin_amdgcn_exp2f(p1[r]);
;   float ps = 0;
; #pragma unroll
;   for (int r = 0; r < 16; ++r) ps += p0[r];
; #pragma unroll
;   for (int r = 0; r < 16; ++r) ps += p1[r];
;   { auto rr = __builtin_amdgcn_permlane32_swap(__float_as_uint(ps), __float_as_uint(ps), false, false);
;     ps = __uint_as_float(rr[0]) + __uint_as_float(rr[1]); }
;   l_reg = l_reg * alpha + ps;
;     ...
;   PK4(p0, 0, pa0); PK4(p0, 8, pa1); PK4(p1, 0, pa2); PK4(p1, 8, pa3);
; __device__ __forceinline__ void qkt(f32x16& p0, f32x16& p1, const bf16_t* Ks, const bf16x8* qr, int r32, int hi) {
;   p0 = f32x16{}; p1 = f32x16{};
; #pragma unroll
;   for (int d0 = 0; d0 < 8; ++d0) { int cb = (d0 * 16 + hi * 8) * 2;
;     bf16x8 b0 = *reinterpret_cast<const bf16x8*>((const char*)Ks + KSWZ(r32, cb));
;     bf16x8 b1 = *reinterpret_cast<const bf16x8*>((const char*)Ks + KSWZ(32 + r32, cb));
;     p0 = __builtin_amdgcn_mfma_f32_32x32x16_bf16(b0, qr[d0], p0, 0, 0, 0);
;     p1 = __builtin_amdgcn_mfma_f32_32x32x16_bf16(b1, qr[d0], p1, 0, 0, 0); }
; }
.Lda_noresc_2:
	v_exp_f32_e32 v80, v80
	v_exp_f32_e32 v81, v81
	v_exp_f32_e32 v82, v82
	v_exp_f32_e32 v83, v83
	v_exp_f32_e32 v84, v84
	v_exp_f32_e32 v85, v85
	v_exp_f32_e32 v86, v86
	v_exp_f32_e32 v87, v87
	v_exp_f32_e32 v88, v88
	v_exp_f32_e32 v89, v89
	v_exp_f32_e32 v90, v90
	v_exp_f32_e32 v91, v91
	v_exp_f32_e32 v92, v92
	v_exp_f32_e32 v93, v93
	v_exp_f32_e32 v94, v94
	v_exp_f32_e32 v95, v95
	v_exp_f32_e32 v64, v64
	v_exp_f32_e32 v65, v65
	v_exp_f32_e32 v66, v66
	v_exp_f32_e32 v67, v67
	v_exp_f32_e32 v68, v68
	v_exp_f32_e32 v69, v69
	v_exp_f32_e32 v70, v70
	v_exp_f32_e32 v71, v71
	v_exp_f32_e32 v72, v72
	v_exp_f32_e32 v73, v73
	v_exp_f32_e32 v74, v74
	v_exp_f32_e32 v75, v75
	v_exp_f32_e32 v76, v76
	v_exp_f32_e32 v77, v77
	v_exp_f32_e32 v78, v78
	v_exp_f32_e32 v79, v79
	v_add_f32_e32 v190, v80, v81
	v_add_f32_e32 v191, v82, v83
	v_add_f32_e32 v190, v190, v84
	v_add_f32_e32 v191, v191, v85
	v_add_f32_e32 v190, v190, v86
	v_add_f32_e32 v191, v191, v87
	v_add_f32_e32 v190, v190, v88
	v_add_f32_e32 v191, v191, v89
	v_add_f32_e32 v190, v190, v90
	v_add_f32_e32 v191, v191, v91
	v_add_f32_e32 v190, v190, v92
	v_add_f32_e32 v191, v191, v93
	v_add_f32_e32 v190, v190, v94
	v_add_f32_e32 v191, v191, v95
	v_add_f32_e32 v190, v190, v64
	v_add_f32_e32 v191, v191, v65
	v_add_f32_e32 v190, v190, v66
	v_add_f32_e32 v191, v191, v67
	v_add_f32_e32 v190, v190, v68
	v_add_f32_e32 v191, v191, v69
	v_add_f32_e32 v190, v190, v70
	v_add_f32_e32 v191, v191, v71
	v_add_f32_e32 v190, v190, v72
	v_add_f32_e32 v191, v191, v73
	v_add_f32_e32 v190, v190, v74
	v_add_f32_e32 v191, v191, v75
	v_add_f32_e32 v190, v190, v76
	v_add_f32_e32 v191, v191, v77
	v_add_f32_e32 v190, v190, v78
	v_add_f32_e32 v191, v191, v79
	v_add_f32_e32 v190, v190, v191
	v_cvt_pk_bf16_f32 v166, v80, v81
	v_cvt_pk_bf16_f32 v167, v82, v83
	v_cvt_pk_bf16_f32 v168, v84, v85
	v_cvt_pk_bf16_f32 v169, v86, v87
	v_cvt_pk_bf16_f32 v170, v88, v89
	v_cvt_pk_bf16_f32 v171, v90, v91
	v_cvt_pk_bf16_f32 v172, v92, v93
	v_cvt_pk_bf16_f32 v173, v94, v95
	v_cvt_pk_bf16_f32 v176, v64, v65
	v_cvt_pk_bf16_f32 v177, v66, v67
	v_cvt_pk_bf16_f32 v178, v68, v69
	v_cvt_pk_bf16_f32 v179, v70, v71
	v_cvt_pk_bf16_f32 v180, v72, v73
	v_cvt_pk_bf16_f32 v181, v74, v75
	v_cvt_pk_bf16_f32 v182, v76, v77
	v_cvt_pk_bf16_f32 v183, v78, v79
	v_permlane32_swap_b32_e32 v166, v168
	v_permlane32_swap_b32_e32 v167, v169
	v_permlane32_swap_b32_e32 v170, v172
	v_permlane32_swap_b32_e32 v171, v173
	v_permlane32_swap_b32_e32 v176, v178
	v_permlane32_swap_b32_e32 v177, v179
	v_permlane32_swap_b32_e32 v180, v182
	v_permlane32_swap_b32_e32 v181, v183
	v_add_f32_e32 v175, v175, v190
	s_add_u32 s31, s31, 1
	s_cmp_lt_u32 s31, 132
	s_cbranch_scc0 .Lda_skipk_2
	ds_read_b128 v[150:153], v204 offset:49152
	ds_read_b128 v[154:157], v204 offset:57344
	ds_read_b128 v[158:161], v205 offset:49152
	ds_read_b128 v[162:165], v205 offset:57344
	ds_read_b128 v[228:231], v206 offset:49152
	ds_read_b128 v[232:235], v206 offset:57344
	ds_read_b128 v[236:239], v207 offset:49152
	ds_read_b128 v[240:243], v207 offset:57344
.Lda_skipk_2:
	s_barrier
	s_setprio 3
	s_waitcnt vmcnt(4)
	ds_write_b128 v197, v[186:189] offset:16384
	ds_write_b128 v197, v[220:223] offset:24576
	ds_write_b128 v185, v[246:249] offset:16384
	ds_write_b128 v185, v[200:203] offset:24576
	s_waitcnt lgkmcnt(10)
	v_mfma_f32_32x32x16_bf16 v[80:95], v[150:153], v[130:133], 0
	v_mfma_f32_32x32x16_bf16 v[64:79], v[154:157], v[130:133], 0
	global_load_dwordx4 v[186:189], v184, s[16:17]
	global_load_dwordx4 v[220:223], v184, s[2:3]
	global_load_dwordx4 v[246:249], v184, s[14:15]
	global_load_dwordx4 v[200:203], v184, s[10:11]
	s_add_u32 s16, s16, 0x60000
	s_addc_u32 s17, s17, 0
	s_add_u32 s2, s2, 0x60000
	s_addc_u32 s3, s3, 0
	s_add_u32 s14, s14, 0x60000
	s_addc_u32 s15, s15, 0
	s_add_u32 s10, s10, 0x60000
	s_addc_u32 s11, s11, 0
	ds_read_b128 v[150:153], v208 offset:49152
	ds_read_b128 v[154:157], v208 offset:57344
	s_waitcnt lgkmcnt(10)
	v_mfma_f32_32x32x16_bf16 v[80:95], v[158:161], v[126:129], v[80:95]
	v_mfma_f32_32x32x16_bf16 v[64:79], v[162:165], v[126:129], v[64:79]
	ds_read_b128 v[158:161], v209 offset:49152
	ds_read_b128 v[162:165], v209 offset:57344
	s_waitcnt lgkmcnt(10)
	v_mfma_f32_32x32x16_bf16 v[80:95], v[228:231], v[122:125], v[80:95]
	v_mfma_f32_32x32x16_bf16 v[64:79], v[232:235], v[122:125], v[64:79]
	ds_read_b128 v[228:231], v210 offset:49152
	ds_read_b128 v[232:235], v210 offset:57344
	s_waitcnt lgkmcnt(10)
	v_mfma_f32_32x32x16_bf16 v[80:95], v[236:239], v[118:121], v[80:95]
	v_mfma_f32_32x32x16_bf16 v[64:79], v[240:243], v[118:121], v[64:79]
	ds_read_b128 v[236:239], v211 offset:49152
	ds_read_b128 v[240:243], v211 offset:57344
	s_waitcnt lgkmcnt(6)
	v_mfma_f32_32x32x16_bf16 v[80:95], v[150:153], v[114:117], v[80:95]
	v_mfma_f32_32x32x16_bf16 v[64:79], v[154:157], v[114:117], v[64:79]
	ds_read_b64_tr_b16 v[150:151], v196 offset:32768
	ds_read_b64_tr_b16 v[152:153], v196 offset:34816
	ds_read_b64_tr_b16 v[154:155], v196 offset:36864
	ds_read_b64_tr_b16 v[156:157], v196 offset:38912
	s_waitcnt lgkmcnt(8)
	v_mfma_f32_32x32x16_bf16 v[80:95], v[158:161], v[110:113], v[80:95]
	v_mfma_f32_32x32x16_bf16 v[64:79], v[162:165], v[110:113], v[64:79]
	ds_read_b64_tr_b16 v[158:159], v196 offset:40960
	ds_read_b64_tr_b16 v[160:161], v196 offset:43008
	ds_read_b64_tr_b16 v[162:163], v196 offset:45056
	ds_read_b64_tr_b16 v[164:165], v196 offset:47104
	s_waitcnt lgkmcnt(10)
; #define SBAR() __builtin_amdgcn_sched_barrier(0)
; __device__ __forceinline__ void partialSM(f32x16& p0, f32x16& p1, float& m_reg, float& mn, float& alpha) {
;   constexpr float C = SCALE * 1.4426950408889634f;
;   float pmax = p0[0];
; #pragma unroll
;   for (int r = 1; r < 16; ++r) pmax = fmaxf(pmax, p0[r]);
; #pragma unroll
;   for (int r = 0; r < 16; ++r) pmax = fmaxf(pmax, p1[r]);
;   { auto rr = __builtin_amdgcn_permlane32_swap(__float_as_uint(pmax), __float_as_uint(pmax), false, false);
;     pmax = fmaxf(__uint_as_float(rr[0]), __uint_as_float(rr[1])); }
;   if (__builtin_expect(__all(pmax - m_reg <= THR / SCALE), 1)) { mn = m_reg; alpha = 1.f; }
;   else { mn = fmaxf(m_reg, pmax); alpha = __builtin_amdgcn_exp2f((m_reg - mn) * C); m_reg = mn; }
; template <int D0> __device__ __forceinline__ void pv_one(f32x16& od, int vb, bf16x8 pa0, bf16x8 pa1, bf16x8 pa2, bf16x8 pa3) {
;   const s16x4 l0 = tr_read<v_rd_off(D0, 0, 0)>(vb), h0 = tr_read<v_rd_off(D0, 0, 1)>(vb), l1 = tr_read<v_rd_off(D0, 1, 0)>(vb), h1 = tr_read<v_rd_off(D0, 1, 1)>(vb);
;   const s16x4 l2 = tr_read<v_rd_off(D0, 2, 0)>(vb), h2 = tr_read<v_rd_off(D0, 2, 1)>(vb), l3 = tr_read<v_rd_off(D0, 3, 0)>(vb), h3 = tr_read<v_rd_off(D0, 3, 1)>(vb);
;   asm volatile("s_waitcnt lgkmcnt(0)" ::: "memory"); SBAR();
;     ...
;   od = __builtin_amdgcn_mfma_f32_32x32x16_bf16(pa0, PK(l0, h0), od, 0, 0, 0);
;   od = __builtin_amdgcn_mfma_f32_32x32x16_bf16(pa1, PK(l1, h1), od, 0, 0, 0);
;   od = __builtin_amdgcn_mfma_f32_32x32x16_bf16(pa2, PK(l2, h2), od, 0, 0, 0);
;   od = __builtin_amdgcn_mfma_f32_32x32x16_bf16(pa3, PK(l3, h3), od, 0, 0, 0);
;     ...
; }
; __device__ __forceinline__ void pv_d0(f32x16* o, int vb, bf16x8 pa0, bf16x8 pa1, bf16x8 pa2, bf16x8 pa3) {
;   pv_one<0>(o[0], vb, pa0, pa1, pa2, pa3); pv_one<1>(o[1], vb, pa0, pa1, pa2, pa3); pv_one<2>(o[2], vb, pa0, pa1, pa2, pa3); pv_one<3>(o[3], vb, pa0, pa1, pa2, pa3);
	v_mfma_f32_32x32x16_bf16 v[80:95], v[228:231], v[106:109], v[80:95]
	v_mfma_f32_32x32x16_bf16 v[64:79], v[232:235], v[106:109], v[64:79]
	ds_read_b64_tr_b16 v[228:229], v196 offset:33280
	ds_read_b64_tr_b16 v[230:231], v196 offset:35328
	ds_read_b64_tr_b16 v[232:233], v196 offset:37376
	ds_read_b64_tr_b16 v[234:235], v196 offset:39424
	s_waitcnt lgkmcnt(12)
	v_mfma_f32_32x32x16_bf16 v[80:95], v[236:239], v[102:105], v[80:95]
	v_mfma_f32_32x32x16_bf16 v[64:79], v[240:243], v[102:105], v[64:79]
	ds_read_b64_tr_b16 v[236:237], v196 offset:41472
	ds_read_b64_tr_b16 v[238:239], v196 offset:43520
	s_waitcnt lgkmcnt(12)
	v_mfma_f32_32x32x16_bf16 v[0:15], v[166:169], v[150:153], v[0:15]
	ds_read_b64_tr_b16 v[240:241], v196 offset:45568
	ds_read_b64_tr_b16 v[242:243], v196 offset:47616
	s_waitcnt lgkmcnt(12)
	v_mfma_f32_32x32x16_bf16 v[0:15], v[170:173], v[154:157], v[0:15]
	ds_read_b64_tr_b16 v[150:151], v196 offset:33792
	ds_read_b64_tr_b16 v[152:153], v196 offset:35840
	s_waitcnt lgkmcnt(12)
	v_mfma_f32_32x32x16_bf16 v[0:15], v[176:179], v[158:161], v[0:15]
	ds_read_b64_tr_b16 v[154:155], v196 offset:37888
	ds_read_b64_tr_b16 v[156:157], v196 offset:39936
	s_waitcnt lgkmcnt(12)
	v_mfma_f32_32x32x16_bf16 v[0:15], v[180:183], v[162:165], v[0:15]
	ds_read_b64_tr_b16 v[158:159], v196 offset:41984
	ds_read_b64_tr_b16 v[160:161], v196 offset:44032
	s_waitcnt lgkmcnt(12)
	v_mfma_f32_32x32x16_bf16 v[48:63], v[166:169], v[228:231], v[48:63]
	ds_read_b64_tr_b16 v[162:163], v196 offset:46080
	ds_read_b64_tr_b16 v[164:165], v196 offset:48128
	s_waitcnt lgkmcnt(12)
	v_mfma_f32_32x32x16_bf16 v[48:63], v[170:173], v[232:235], v[48:63]
	ds_read_b64_tr_b16 v[228:229], v196 offset:34304
	ds_read_b64_tr_b16 v[230:231], v196 offset:36352
	s_waitcnt lgkmcnt(12)
	v_mfma_f32_32x32x16_bf16 v[48:63], v[176:179], v[236:239], v[48:63]
	ds_read_b64_tr_b16 v[232:233], v196 offset:38400
	ds_read_b64_tr_b16 v[234:235], v196 offset:40448
	s_waitcnt lgkmcnt(12)
	v_mfma_f32_32x32x16_bf16 v[48:63], v[180:183], v[240:243], v[48:63]
	ds_read_b64_tr_b16 v[236:237], v196 offset:42496
	ds_read_b64_tr_b16 v[238:239], v196 offset:44544
	s_waitcnt lgkmcnt(12)
	v_mfma_f32_32x32x16_bf16 v[32:47], v[166:169], v[150:153], v[32:47]
	ds_read_b64_tr_b16 v[240:241], v196 offset:46592
	ds_read_b64_tr_b16 v[242:243], v196 offset:48640
	s_waitcnt lgkmcnt(12)
	v_mfma_f32_32x32x16_bf16 v[32:47], v[170:173], v[154:157], v[32:47]
	s_waitcnt lgkmcnt(10)
	v_mfma_f32_32x32x16_bf16 v[32:47], v[176:179], v[158:161], v[32:47]
	s_waitcnt lgkmcnt(8)
	v_mfma_f32_32x32x16_bf16 v[32:47], v[180:183], v[162:165], v[32:47]
	s_waitcnt lgkmcnt(6)
	v_mfma_f32_32x32x16_bf16 v[16:31], v[166:169], v[228:231], v[16:31]
	s_waitcnt lgkmcnt(4)
	v_mfma_f32_32x32x16_bf16 v[16:31], v[170:173], v[232:235], v[16:31]
	s_waitcnt lgkmcnt(2)
	v_mfma_f32_32x32x16_bf16 v[16:31], v[176:179], v[236:239], v[16:31]
	s_waitcnt lgkmcnt(0)
	v_mfma_f32_32x32x16_bf16 v[16:31], v[180:183], v[240:243], v[16:31]
	s_setprio 0
	s_barrier
	v_max3_f32 v190, v80, v81, v82
	v_max3_f32 v191, v64, v65, v66
	v_max3_f32 v190, v190, v83, v84
	v_max3_f32 v191, v191, v67, v68
	v_max3_f32 v190, v190, v85, v86
	v_max3_f32 v191, v191, v69, v70
	v_max3_f32 v190, v190, v87, v88
	v_max3_f32 v191, v191, v71, v72
	v_max3_f32 v190, v190, v89, v90
	v_max3_f32 v191, v191, v73, v74
	v_max3_f32 v190, v190, v91, v92
	v_max3_f32 v191, v191, v75, v76
	v_max3_f32 v190, v190, v93, v94
	v_max3_f32 v191, v191, v77, v78
	v_max3_f32 v190, v190, v95, v79
	v_max_f32_e32 v190, v190, v191
	v_sub_f32_e32 v215, v190, v174
	v_cmp_ge_f32_e32 vcc, s86, v215
	s_nop 0
	s_cmp_eq_u64 vcc, exec
	s_cbranch_scc1 .Lda_common_3
	v_mov_b32_e32 v191, v190
	s_nop 1
	v_permlane32_swap_b32_e32 v190, v191
	s_nop 0
	v_max_f32_e32 v212, v190, v191
	v_max_f32_e32 v191, v174, v212
	v_sub_f32_e32 v215, v174, v191
	v_mul_f32_e32 v215, s92, v215
	v_exp_f32_e32 v213, v215
	v_mov_b32_e32 v174, v191
	v_mul_f32_e32 v214, 0xbe0293ee, v174
	v_mul_f32_e32 v175, v175, v213
	s_and_saveexec_b64 s[12:13], s[40:41]
	ds_write_b32 v199, v213 offset:128
	s_or_b64 exec, exec, s[12:13]
	s_waitcnt lgkmcnt(0)
	v_add_u32_e32 v215, v99, v96
	ds_read_b128 v[228:231], v215 offset:128
	ds_read_b128 v[232:235], v215 offset:160
	ds_read_b128 v[236:239], v215 offset:192
	ds_read_b128 v[240:243], v215 offset:224
	s_waitcnt lgkmcnt(0)
	v_pk_mul_f32 v[0:1], v[0:1], v[228:229]
	v_pk_mul_f32 v[2:3], v[2:3], v[230:231]
	v_pk_mul_f32 v[4:5], v[4:5], v[232:233]
	v_pk_mul_f32 v[6:7], v[6:7], v[234:235]
	v_pk_mul_f32 v[8:9], v[8:9], v[236:237]
	v_pk_mul_f32 v[10:11], v[10:11], v[238:239]
	v_pk_mul_f32 v[12:13], v[12:13], v[240:241]
	v_pk_mul_f32 v[14:15], v[14:15], v[242:243]
	v_pk_mul_f32 v[48:49], v[48:49], v[228:229]
	v_pk_mul_f32 v[50:51], v[50:51], v[230:231]
	v_pk_mul_f32 v[52:53], v[52:53], v[232:233]
	v_pk_mul_f32 v[54:55], v[54:55], v[234:235]
	v_pk_mul_f32 v[56:57], v[56:57], v[236:237]
	v_pk_mul_f32 v[58:59], v[58:59], v[238:239]
	v_pk_mul_f32 v[60:61], v[60:61], v[240:241]
	v_pk_mul_f32 v[62:63], v[62:63], v[242:243]
	v_pk_mul_f32 v[32:33], v[32:33], v[228:229]
	v_pk_mul_f32 v[34:35], v[34:35], v[230:231]
	v_pk_mul_f32 v[36:37], v[36:37], v[232:233]
	v_pk_mul_f32 v[38:39], v[38:39], v[234:235]
	v_pk_mul_f32 v[40:41], v[40:41], v[236:237]
	v_pk_mul_f32 v[42:43], v[42:43], v[238:239]
	v_pk_mul_f32 v[44:45], v[44:45], v[240:241]
	v_pk_mul_f32 v[46:47], v[46:47], v[242:243]
	v_pk_mul_f32 v[16:17], v[16:17], v[228:229]
	v_pk_mul_f32 v[18:19], v[18:19], v[230:231]
	v_pk_mul_f32 v[20:21], v[20:21], v[232:233]
	v_pk_mul_f32 v[22:23], v[22:23], v[234:235]
	v_pk_mul_f32 v[24:25], v[24:25], v[236:237]
	v_pk_mul_f32 v[26:27], v[26:27], v[238:239]
	v_pk_mul_f32 v[28:29], v[28:29], v[240:241]
	v_pk_mul_f32 v[30:31], v[30:31], v[242:243]

; __device__ __forceinline__ void finishSM(f32x16& p0, f32x16& p1, float alpha, float& l_reg, bf16x8& pa0, bf16x8& pa1, bf16x8& pa2, bf16x8& pa3) {
; #pragma unroll
;   for (int r = 0; r < 16; ++r) p1[r] = __builtin_amdgcn_exp2f(p1[r]);
;   float ps = 0;
; #pragma unroll
;   for (int r = 0; r < 16; ++r) ps += p0[r];
; #pragma unroll
;   for (int r = 0; r < 16; ++r) ps += p1[r];
;   { auto rr = __builtin_amdgcn_permlane32_swap(__float_as_uint(ps), __float_as_uint(ps), false, false);
;     ps = __uint_as_float(rr[0]) + __uint_as_float(rr[1]); }
;   l_reg = l_reg * alpha + ps;
;     ...
;   PK4(p0, 0, pa0); PK4(p0, 8, pa1); PK4(p1, 0, pa2); PK4(p1, 8, pa3);
.Lda_noresc_3:
	v_exp_f32_e32 v80, v80
	v_exp_f32_e32 v81, v81
	v_exp_f32_e32 v82, v82
	v_exp_f32_e32 v83, v83
	v_exp_f32_e32 v84, v84
	v_exp_f32_e32 v85, v85
	v_exp_f32_e32 v86, v86
	v_exp_f32_e32 v87, v87
	v_exp_f32_e32 v88, v88
	v_exp_f32_e32 v89, v89
	v_exp_f32_e32 v90, v90
	v_exp_f32_e32 v91, v91
	v_exp_f32_e32 v92, v92
	v_exp_f32_e32 v93, v93
	v_exp_f32_e32 v94, v94
	v_exp_f32_e32 v95, v95
	v_exp_f32_e32 v64, v64
	v_exp_f32_e32 v65, v65
	v_exp_f32_e32 v66, v66
	v_exp_f32_e32 v67, v67
	v_exp_f32_e32 v68, v68
	v_exp_f32_e32 v69, v69
	v_exp_f32_e32 v70, v70
	v_exp_f32_e32 v71, v71
	v_exp_f32_e32 v72, v72
	v_exp_f32_e32 v73, v73
	v_exp_f32_e32 v74, v74
	v_exp_f32_e32 v75, v75
	v_exp_f32_e32 v76, v76
	v_exp_f32_e32 v77, v77
	v_exp_f32_e32 v78, v78
	v_exp_f32_e32 v79, v79
	v_add_f32_e32 v190, v80, v81
	v_add_f32_e32 v191, v82, v83
	v_add_f32_e32 v190, v190, v84
	v_add_f32_e32 v191, v191, v85
	v_add_f32_e32 v190, v190, v86
	v_add_f32_e32 v191, v191, v87
	v_add_f32_e32 v190, v190, v88
	v_add_f32_e32 v191, v191, v89
	v_add_f32_e32 v190, v190, v90
	v_add_f32_e32 v191, v191, v91
	v_add_f32_e32 v190, v190, v92
	v_add_f32_e32 v191, v191, v93
	v_add_f32_e32 v190, v190, v94
	v_add_f32_e32 v191, v191, v95
	v_add_f32_e32 v190, v190, v64
	v_add_f32_e32 v191, v191, v65
	v_add_f32_e32 v190, v190, v66
	v_add_f32_e32 v191, v191, v67
	v_add_f32_e32 v190, v190, v68
	v_add_f32_e32 v191, v191, v69
	v_add_f32_e32 v190, v190, v70
	v_add_f32_e32 v191, v191, v71
	v_add_f32_e32 v190, v190, v72
	v_add_f32_e32 v191, v191, v73
	v_add_f32_e32 v190, v190, v74
	v_add_f32_e32 v191, v191, v75
	v_add_f32_e32 v190, v190, v76
	v_add_f32_e32 v191, v191, v77
	v_add_f32_e32 v190, v190, v78
	v_add_f32_e32 v191, v191, v79
	v_add_f32_e32 v190, v190, v191
	v_cvt_pk_bf16_f32 v166, v80, v81
	v_cvt_pk_bf16_f32 v167, v82, v83
	v_cvt_pk_bf16_f32 v168, v84, v85
	v_cvt_pk_bf16_f32 v169, v86, v87
	v_cvt_pk_bf16_f32 v170, v88, v89
	v_cvt_pk_bf16_f32 v171, v90, v91
	v_cvt_pk_bf16_f32 v172, v92, v93
	v_cvt_pk_bf16_f32 v173, v94, v95
	v_cvt_pk_bf16_f32 v176, v64, v65
	v_cvt_pk_bf16_f32 v177, v66, v67
	v_cvt_pk_bf16_f32 v178, v68, v69
	v_cvt_pk_bf16_f32 v179, v70, v71
	v_cvt_pk_bf16_f32 v180, v72, v73
	v_cvt_pk_bf16_f32 v181, v74, v75
	v_cvt_pk_bf16_f32 v182, v76, v77
	v_cvt_pk_bf16_f32 v183, v78, v79
	v_permlane32_swap_b32_e32 v166, v168
	v_permlane32_swap_b32_e32 v167, v169
	v_permlane32_swap_b32_e32 v170, v172
	v_permlane32_swap_b32_e32 v171, v173
	v_permlane32_swap_b32_e32 v176, v178
	v_permlane32_swap_b32_e32 v177, v179
	v_permlane32_swap_b32_e32 v180, v182
	v_permlane32_swap_b32_e32 v181, v183
	v_add_f32_e32 v175, v175, v190
	s_add_u32 s31, s31, 1
	s_cmp_lt_u32 s31, 132
	s_cbranch_scc0 .Lda_skipk_3
	ds_read_b128 v[150:153], v204 offset:0
	ds_read_b128 v[154:157], v204 offset:8192
	ds_read_b128 v[158:161], v205 offset:0
	ds_read_b128 v[162:165], v205 offset:8192
	ds_read_b128 v[228:231], v206 offset:0
	ds_read_b128 v[232:235], v206 offset:8192
	ds_read_b128 v[236:239], v207 offset:0
	ds_read_b128 v[240:243], v207 offset:8192
